# FFN-down GEMMs (P7,P12): per-XCD round covers 4 row panels x 8 column tiles instead of 2 x 16 (on top of mnk order + saddr loads)
# baseline (speedup 1.0000x reference)
.LBB0_2322:
	s_ashr_i32 s3, s3, 3
	s_add_i32 s3, s12, s3
	s_ashr_i32 s4, s3, 31
	s_lshr_b32 s4, s4, 25
	s_add_i32 s4, s3, s4
	s_ashr_i32 s5, s4, 7
	s_and_b32 s4, s4, 0xffffff80
	s_sub_i32 s4, s3, s4
	s_and_b32 s3, s4, 3
	s_bfe_u32 s7, s4, 0x10005
	s_lshl_b32 s7, s7, 2
	s_add_i32 s7, s3, s7
	s_lshl_b32 s5, s5, 3
	s_add_i32 s3, s5, s7
	s_bfe_u32 s33, s4, 0x30002
	s_lshr_b32 s7, s4, 6
	s_lshl_b32 s7, s7, 3
	s_add_i32 s33, s33, s7

.LBB0_2334:
	s_ashr_i32 s6, s12, 3
	s_add_i32 s6, s39, s6
	s_ashr_i32 s7, s6, 31
	s_lshr_b32 s7, s7, 25
	s_add_i32 s7, s6, s7
	s_ashr_i32 s12, s7, 7
	s_and_b32 s7, s7, 0xff80
	s_sub_i32 s6, s6, s7
	s_and_b32 s68, s6, 3
	s_bfe_u32 s7, s6, 0x10005
	s_lshl_b32 s7, s7, 2
	s_add_i32 s7, s68, s7
	s_lshl_b32 s12, s12, 3
	s_add_i32 s68, s12, s7
	s_bfe_u32 s69, s6, 0x30002
	s_lshr_b32 s7, s6, 6
	s_lshl_b32 s7, s7, 3
	s_add_i32 s69, s69, s7

.LBB0_2787:
	s_add_i32 s3, s7, s4
	s_ashr_i32 s4, s3, 31
	s_lshr_b32 s4, s4, 25
	s_add_i32 s4, s3, s4
	s_ashr_i32 s5, s4, 7
	s_and_b32 s4, s4, 0xff80
	s_sub_i32 s4, s3, s4
	s_and_b32 s3, s4, 3
	s_bfe_u32 s7, s4, 0x10005
	s_lshl_b32 s7, s7, 2
	s_add_i32 s7, s3, s7
	s_lshl_b32 s5, s5, 3
	s_add_i32 s3, s5, s7
	s_bfe_u32 s33, s4, 0x30002
	s_lshr_b32 s7, s4, 6
	s_lshl_b32 s7, s7, 3
	s_add_i32 s33, s33, s7

.LBB0_2799:
	s_ashr_i32 s4, s12, 3
	s_add_i32 s4, s25, s4
	s_ashr_i32 s5, s4, 31
	s_lshr_b32 s5, s5, 25
	s_add_i32 s5, s4, s5
	s_ashr_i32 s12, s5, 7
	s_and_b32 s5, s5, 0xff80
	s_sub_i32 s4, s4, s5
	s_and_b32 s50, s4, 3
	s_bfe_u32 s5, s4, 0x10005
	s_lshl_b32 s5, s5, 2
	s_add_i32 s5, s50, s5
	s_lshl_b32 s12, s12, 3
	s_add_i32 s50, s12, s5
	s_bfe_u32 s51, s4, 0x30002
	s_lshr_b32 s5, s4, 6
	s_lshl_b32 s5, s5, 3
	s_add_i32 s51, s51, s5
